# ping-pong MLA loop plus all 12 K-fragment LDS reads issued at the loop head into own registers, V-fragment reads fed between the QK MFMA pairs, all DMA of waves 0-3 at the head
# baseline (speedup 1.0000x reference)
.LBB0_350:
	s_add_i32 s0, s2, -1
	s_and_b32 s3, s0, 1
	s_xor_b32 s0, s3, 1
	s_mulk_i32 s0, 0x5100
	v_add_u32_e32 v84, s0, v197
	ds_read_b128 v[18:21], v84
	ds_read_b128 v[22:25], v84 offset:512
	ds_read_b128 v[220:223], v84 offset:2048
	ds_read_b128 v[224:227], v84 offset:2560
	ds_read_b128 v[228:231], v84 offset:4096
	ds_read_b128 v[232:235], v84 offset:4608
	ds_read_b128 v[236:239], v84 offset:6144
	ds_read_b128 v[240:243], v84 offset:6656
	ds_read_b128 v[244:247], v84 offset:8192
	ds_read_b128 v[208:211], v84 offset:8704
	ds_read_b128 v[200:203], v84 offset:10240
	ds_read_b128 v[204:207], v84 offset:10752
	v_add_u32_e32 v115, s0, v196
	s_and_b64 vcc, exec, s[38:39]
	s_cbranch_vccnz .LBB0_352
	s_mov_b32 m0, s101
	v_mov_b32_e32 v26, v114
	global_load_lds_dwordx4 v[216:217], off
	s_add_i32 m0, s101, 0x2000
	v_ashrrev_i32_e32 v27, 31, v114
	global_load_lds_dwordx4 v[218:219], off
	v_lshlrev_b64 v[26:27], 11, v[26:27]
	s_add_i32 m0, s101, 0x2f80
	v_lshl_add_u64 v[26:27], v[30:31], 0, v[26:27]
	global_load_lds_dwordx4 v[26:27], off offset:128
.LBB0_352:
	s_waitcnt lgkmcnt(10)
	v_mfma_f32_32x32x16_bf16 v[2:17], v[18:21], v[116:119], v[96:111]
	v_mfma_f32_32x32x16_bf16 v[64:79], v[22:25], v[116:119], v[96:111]
	ds_read_b64_tr_b16 v[152:153], v115 offset:12288
	ds_read_b64_tr_b16 v[154:155], v115 offset:12800
	ds_read_b64_tr_b16 v[88:89], v115 offset:13312
	ds_read_b64_tr_b16 v[90:91], v115 offset:13824
	s_waitcnt lgkmcnt(12)
	v_mfma_f32_32x32x16_bf16 v[64:79], v[224:227], v[120:123], v[64:79]
	v_mfma_f32_32x32x16_bf16 v[2:17], v[220:223], v[120:123], v[2:17]
	ds_read_b64_tr_b16 v[80:81], v115 offset:14336
	ds_read_b64_tr_b16 v[82:83], v115 offset:14848
	ds_read_b64_tr_b16 v[18:19], v115 offset:15360
	s_waitcnt lgkmcnt(13)
	v_mfma_f32_32x32x16_bf16 v[64:79], v[232:235], v[124:127], v[64:79]
	v_mfma_f32_32x32x16_bf16 v[2:17], v[228:231], v[124:127], v[2:17]
	ds_read_b64_tr_b16 v[20:21], v115 offset:15872
	ds_read_b64_tr_b16 v[92:93], v115 offset:16384
	s_waitcnt lgkmcnt(13)
	v_mfma_f32_32x32x16_bf16 v[64:79], v[240:243], v[128:131], v[64:79]
	v_mfma_f32_32x32x16_bf16 v[2:17], v[236:239], v[128:131], v[2:17]
	ds_read_b64_tr_b16 v[94:95], v115 offset:16896
	ds_read_b64_tr_b16 v[84:85], v115 offset:17408
	s_waitcnt lgkmcnt(13)
	v_mfma_f32_32x32x16_bf16 v[64:79], v[208:211], v[132:135], v[64:79]
	v_mfma_f32_32x32x16_bf16 v[2:17], v[244:247], v[132:135], v[2:17]
	ds_read_b64_tr_b16 v[86:87], v115 offset:17920
	ds_read_b64_tr_b16 v[26:27], v115 offset:18432
	s_waitcnt lgkmcnt(13)
	ds_read_b64_tr_b16 v[28:29], v115 offset:18944
	ds_read_b64_tr_b16 v[22:23], v115 offset:19456
	v_mfma_f32_32x32x16_bf16 v[2:17], v[200:203], v[136:139], v[2:17]
	v_mfma_f32_32x32x16_bf16 v[64:79], v[204:207], v[136:139], v[64:79]
	s_waitcnt lgkmcnt(14)
	ds_read_b64_tr_b16 v[24:25], v115 offset:19968
	s_and_b64 vcc, exec, s[38:39]
	s_cbranch_vccnz .Lpp_midB
	s_barrier
	s_branch .Lpp_mid_done

.LBB0_356:
	v_exp_f32_e32 v115, v2
	v_exp_f32_e32 v171, v3
	v_exp_f32_e32 v200, v4
	v_exp_f32_e32 v201, v5
	v_exp_f32_e32 v6, v6
	v_exp_f32_e32 v7, v7
	v_exp_f32_e32 v8, v8
	v_exp_f32_e32 v9, v9
	v_cvt_pk_bf16_f32 v202, v115, v171
	v_cvt_pk_bf16_f32 v203, v200, v201
	v_cvt_pk_bf16_f32 v204, v6, v7
	v_cvt_pk_bf16_f32 v205, v8, v9
	v_exp_f32_e32 v10, v10
	v_exp_f32_e32 v11, v11
	v_exp_f32_e32 v12, v12
	v_exp_f32_e32 v13, v13
	v_exp_f32_e32 v14, v14
	v_exp_f32_e32 v15, v15
	v_exp_f32_e32 v16, v16
	v_exp_f32_e32 v17, v17
	s_waitcnt lgkmcnt(14)
	v_mfma_f32_32x32x16_bf16 v[32:47], v[202:205], v[152:155], v[32:47]
	v_cvt_pk_bf16_f32 v206, v10, v11
	v_cvt_pk_bf16_f32 v207, v12, v13
	v_cvt_pk_bf16_f32 v208, v14, v15
	v_cvt_pk_bf16_f32 v209, v16, v17
	v_exp_f32_e32 v64, v64
	v_exp_f32_e32 v65, v65
	v_exp_f32_e32 v66, v66
	s_waitcnt lgkmcnt(6)
	v_mfma_f32_32x32x16_bf16 v[48:63], v[202:205], v[92:95], v[48:63]
	v_exp_f32_e32 v67, v67
	v_exp_f32_e32 v68, v68
	v_exp_f32_e32 v69, v69
	v_exp_f32_e32 v70, v70
	v_exp_f32_e32 v71, v71
	v_cvt_pk_bf16_f32 v210, v64, v65
	v_cvt_pk_bf16_f32 v211, v66, v67
	v_mfma_f32_32x32x16_bf16 v[32:47], v[206:209], v[88:91], v[32:47]
	v_cvt_pk_bf16_f32 v212, v68, v69
	v_cvt_pk_bf16_f32 v213, v70, v71
	v_exp_f32_e32 v72, v72
	v_exp_f32_e32 v73, v73
	v_exp_f32_e32 v74, v74
	v_exp_f32_e32 v75, v75
	v_exp_f32_e32 v76, v76
	s_waitcnt lgkmcnt(4)
	v_mfma_f32_32x32x16_bf16 v[48:63], v[206:209], v[84:87], v[48:63]
	v_exp_f32_e32 v77, v77
	v_exp_f32_e32 v78, v78
	v_exp_f32_e32 v79, v79
	v_cvt_pk_bf16_f32 v2, v72, v73
	v_cvt_pk_bf16_f32 v3, v74, v75
	v_cvt_pk_bf16_f32 v4, v76, v77
	v_cvt_pk_bf16_f32 v5, v78, v79
	v_mfma_f32_32x32x16_bf16 v[32:47], v[210:213], v[80:83], v[32:47]
	s_mulk_i32 s3, 0x5100
	s_and_b64 vcc, exec, s[38:39]
	s_waitcnt lgkmcnt(2)
	v_mfma_f32_32x32x16_bf16 v[48:63], v[210:213], v[26:29], v[48:63]
	v_mfma_f32_32x32x16_bf16 v[32:47], v[2:5], v[18:21], v[32:47]
	s_waitcnt lgkmcnt(0)
	v_mfma_f32_32x32x16_bf16 v[48:63], v[2:5], v[22:25], v[48:63]
	s_branch .LBB0_349
